# MLA first call: late waves run softmax(kt-1) at the start of iteration kt, then P.V(kt-1), then S(kt) (scores carried across the tile barrier)
# speedup vs baseline: 1.0064x; 1.0064x over previous
; DI float xhalf_max(float x) { float lo, hi; xhalf(x, lo, hi); return fmaxf(lo, hi); }
; DI void mla_s_softmax(const LAS unsigned char* base, int r, int h, bool is_diag, int lim, const bf16x8 (&qf)[12], f32x16 (&o)[4], float& m_run, float& l_run,
;                       bf16x8 (&pf0)[2], bf16x8 (&pf1)[2]) {
;     ...
;     if (is_diag) {
; #pragma unroll
;         for (int i = 0; i < 16; ++i) { if (16 * h + i > lim) s0[i] = -1e30f; if (32 + 16 * h + i > lim) s1[i] = -1e30f; }
;     }
;     float mx = fmaxf(s0[0], s1[0]);
; #pragma unroll
;     for (int i = 1; i < 16; ++i) mx = fmaxf(mx, fmaxf(s0[i], s1[i]));
;     mx = xhalf_max(mx);
;     const float mnew = fmaxf(m_run, mx);
;     if (__builtin_amdgcn_ballot_w64(mnew > m_run + 8.0f) != 0ull) {
;         const float alpha = __builtin_amdgcn_exp2f(m_run - mnew);
;         l_run *= alpha;
; #pragma unroll
;         for (int dt = 0; dt < 4; ++dt) o[dt] *= alpha;
;         m_run = mnew;
;     }
.LBB0_635:
	s_cmp_lg_u32 s77, 0
	s_cselect_b64 s[90:91], -1, 0
	s_and_b64 s[90:91], s[78:79], s[90:91]
	s_cmp_le_i32 s77, s84
	s_cselect_b64 vcc, -1, 0
	s_and_b64 s[90:91], s[90:91], vcc
	s_andn2_b64 vcc, exec, s[90:91]
	s_mul_i32 s89, s73, 0xac00
	s_cbranch_vccnz .LBB0_638
	s_cmp_eq_u32 s84, s77
	s_cselect_b32 s100, 1, 0
	s_mov_b32 s101, 0
.Lmla_lsm_0:
	s_cmp_lg_u32 s100, 1
	s_cbranch_scc1 .Lmla_lsm_nomask_0
	v_readlane_b32 s90, v255, 49
	v_readlane_b32 s91, v255, 50
	s_nop 8
	v_cndmask_b32_e64 v80, v80, v164, s[6:7]
	v_cndmask_b32_e64 v97, v164, v97, s[8:9]
	v_cndmask_b32_e64 v0, v96, v164, s[90:91]
	v_cndmask_b32_e64 v96, v0, v96, s[8:9]
	v_cndmask_b32_e64 v81, v81, v164, s[10:11]
	v_cndmask_b32_e64 v98, v98, v164, s[86:87]
	v_cndmask_b32_e64 v82, v82, v164, s[4:5]
	v_cndmask_b32_e64 v99, v99, v164, s[16:17]
	v_cndmask_b32_e64 v83, v83, v164, s[18:19]
	v_cndmask_b32_e64 v100, v100, v164, s[20:21]
	v_cndmask_b32_e64 v84, v84, v164, s[22:23]
	v_cndmask_b32_e64 v101, v101, v164, s[24:25]
	v_cndmask_b32_e64 v85, v85, v164, s[26:27]
	v_cndmask_b32_e64 v102, v102, v164, s[28:29]
	v_cndmask_b32_e64 v86, v86, v164, s[30:31]
	v_cndmask_b32_e64 v103, v103, v164, s[34:35]
	v_cndmask_b32_e64 v87, v87, v164, s[36:37]
	v_cndmask_b32_e64 v104, v104, v164, s[38:39]
	v_cndmask_b32_e64 v88, v88, v164, s[40:41]
	v_cndmask_b32_e64 v105, v105, v164, s[42:43]
	v_cndmask_b32_e64 v89, v89, v164, s[44:45]
	v_cndmask_b32_e64 v106, v106, v164, s[46:47]
	v_cndmask_b32_e64 v90, v90, v164, s[48:49]
	v_cndmask_b32_e64 v107, v107, v164, s[50:51]
	v_cndmask_b32_e64 v91, v91, v164, s[52:53]
	v_cndmask_b32_e64 v108, v108, v164, s[54:55]
	v_cndmask_b32_e64 v92, v92, v164, s[56:57]
	v_cndmask_b32_e64 v109, v109, v164, s[58:59]
	v_cndmask_b32_e64 v93, v93, v164, s[60:61]
	v_cndmask_b32_e64 v110, v110, v164, s[62:63]
	v_cndmask_b32_e64 v94, v94, v164, s[64:65]
	v_cndmask_b32_e64 v111, v111, v164, s[66:67]
	v_cndmask_b32_e64 v95, v95, v164, s[68:69]
.Lmla_lsm_nomask_0:
	v_max3_f32 v0, v80, v81, v82
	v_max3_f32 v2, v96, v97, v98
	v_max3_f32 v0, v0, v83, v84
	v_max3_f32 v2, v2, v99, v100
	v_max3_f32 v0, v0, v85, v86
	v_max3_f32 v2, v2, v101, v102
	v_max3_f32 v0, v0, v87, v88
	v_max3_f32 v2, v2, v103, v104
	v_max3_f32 v0, v0, v89, v90
	v_max3_f32 v2, v2, v105, v106
	v_max3_f32 v0, v0, v91, v92
	v_max3_f32 v2, v2, v107, v108
	v_max3_f32 v0, v0, v93, v94
	v_max3_f32 v2, v2, v109, v110
	v_max3_f32 v0, v0, v95, v111
	v_max_f32_e32 v0, v0, v2
	v_mov_b32_e32 v2, v0
	s_nop 1
	v_permlane32_swap_b32_e32 v0, v2
	v_max3_f32 v0, v183, v0, v2
	v_add_f32_e32 v2, 0x41000000, v183
	v_cmp_gt_f32_e32 vcc, v0, v2
	s_cbranch_vccz .Lmla_lsm_643_0
	v_sub_f32_e32 v2, v183, v0
	v_exp_f32_e32 v2, v2
	v_mov_b32_e32 v183, v0
	v_mul_f32_e32 v175, v175, v2
	v_pk_mul_f32 v[78:79], v[78:79], v[2:3] op_sel_hi:[1,0]
	v_pk_mul_f32 v[76:77], v[76:77], v[2:3] op_sel_hi:[1,0]
	v_pk_mul_f32 v[74:75], v[74:75], v[2:3] op_sel_hi:[1,0]
	v_pk_mul_f32 v[72:73], v[72:73], v[2:3] op_sel_hi:[1,0]
	v_pk_mul_f32 v[70:71], v[70:71], v[2:3] op_sel_hi:[1,0]
	v_pk_mul_f32 v[68:69], v[68:69], v[2:3] op_sel_hi:[1,0]
	v_pk_mul_f32 v[66:67], v[66:67], v[2:3] op_sel_hi:[1,0]
	v_pk_mul_f32 v[64:65], v[64:65], v[2:3] op_sel_hi:[1,0]
	v_pk_mul_f32 v[62:63], v[62:63], v[2:3] op_sel_hi:[1,0]
	v_pk_mul_f32 v[60:61], v[60:61], v[2:3] op_sel_hi:[1,0]
	v_pk_mul_f32 v[58:59], v[58:59], v[2:3] op_sel_hi:[1,0]
	v_pk_mul_f32 v[56:57], v[56:57], v[2:3] op_sel_hi:[1,0]
	v_pk_mul_f32 v[54:55], v[54:55], v[2:3] op_sel_hi:[1,0]
	v_pk_mul_f32 v[52:53], v[52:53], v[2:3] op_sel_hi:[1,0]
	v_pk_mul_f32 v[50:51], v[50:51], v[2:3] op_sel_hi:[1,0]
	v_pk_mul_f32 v[48:49], v[48:49], v[2:3] op_sel_hi:[1,0]
	v_pk_mul_f32 v[46:47], v[46:47], v[2:3] op_sel_hi:[1,0]
	v_pk_mul_f32 v[44:45], v[44:45], v[2:3] op_sel_hi:[1,0]
	v_pk_mul_f32 v[42:43], v[42:43], v[2:3] op_sel_hi:[1,0]
	v_pk_mul_f32 v[40:41], v[40:41], v[2:3] op_sel_hi:[1,0]
	v_pk_mul_f32 v[38:39], v[38:39], v[2:3] op_sel_hi:[1,0]
	v_pk_mul_f32 v[36:37], v[36:37], v[2:3] op_sel_hi:[1,0]
	v_pk_mul_f32 v[34:35], v[34:35], v[2:3] op_sel_hi:[1,0]
	v_pk_mul_f32 v[32:33], v[32:33], v[2:3] op_sel_hi:[1,0]
	v_pk_mul_f32 v[30:31], v[30:31], v[2:3] op_sel_hi:[1,0]
	v_pk_mul_f32 v[28:29], v[28:29], v[2:3] op_sel_hi:[1,0]
	v_pk_mul_f32 v[26:27], v[26:27], v[2:3] op_sel_hi:[1,0]
	v_pk_mul_f32 v[24:25], v[24:25], v[2:3] op_sel_hi:[1,0]
	v_pk_mul_f32 v[22:23], v[22:23], v[2:3] op_sel_hi:[1,0]
	v_pk_mul_f32 v[20:21], v[20:21], v[2:3] op_sel_hi:[1,0]
	v_pk_mul_f32 v[18:19], v[18:19], v[2:3] op_sel_hi:[1,0]
	v_pk_mul_f32 v[16:17], v[16:17], v[2:3] op_sel_hi:[1,0]
; #define LAS __attribute__((address_space(3)))
; DI unsigned pk2(float lo, float hi) { f32x2 v = {lo, hi}; bf2_t r = __builtin_convertvector(v, bf2_t); return __builtin_bit_cast(unsigned, r); }
; #define MFMA32(a, b, c) __builtin_amdgcn_mfma_f32_32x32x16_bf16((a), (b), (c), 0, 0, 0)
; DI void mla_s_softmax(const LAS unsigned char* base, int r, int h, bool is_diag, int lim, const bf16x8 (&qf)[12], f32x16 (&o)[4], float& m_run, float& l_run,
;                       bf16x8 (&pf0)[2], bf16x8 (&pf1)[2]) {
;     ...
;     float ls = 0.f;
; #pragma unroll
;     for (int i = 0; i < 16; ++i) { s0[i] = __builtin_amdgcn_exp2f(s0[i] - m_run); s1[i] = __builtin_amdgcn_exp2f(s1[i] - m_run); ls += s0[i] + s1[i]; }
;     l_run += ls;
; #pragma unroll
;     for (int s = 0; s < 2; ++s) {
;         u32x4 a, c;
;         a.x = pk2(s0[8 * s + 0], s0[8 * s + 1]); a.y = pk2(s0[8 * s + 2], s0[8 * s + 3]); a.z = pk2(s0[8 * s + 4], s0[8 * s + 5]); a.w = pk2(s0[8 * s + 6], s0[8 * s + 7]);
;         c.x = pk2(s1[8 * s + 0], s1[8 * s + 1]); c.y = pk2(s1[8 * s + 2], s1[8 * s + 3]); c.z = pk2(s1[8 * s + 4], s1[8 * s + 5]); c.w = pk2(s1[8 * s + 6], s1[8 * s + 7]);
;         pf0[s] = __builtin_bit_cast(bf16x8, a); pf1[s] = __builtin_bit_cast(bf16x8, c);
;     }
; }
; DI void mla_pv(const LAS unsigned char* base, int r, int h, const bf16x8 (&pf0)[2], const bf16x8 (&pf1)[2], f32x16 (&o)[4]) {
;     const LAS unsigned char* vp = base + MLA_KBYTES + r * MLA_VROW + h * 32;
; #pragma unroll
;     for (int s = 0; s < 2; ++s) {
;         bf16x8 va[4], vb[4];
; #pragma unroll
;         for (int dt = 0; dt < 4; ++dt) { va[dt] = *(const LAS bf16x8*)(vp + dt * 32 * MLA_VROW + s * 16); vb[dt] = *(const LAS bf16x8*)(vp + dt * 32 * MLA_VROW + 64 + s * 16); }
;         __builtin_amdgcn_sched_barrier(0);
; #pragma unroll
;         for (int dt = 0; dt < 4; ++dt) o[dt] = MFMA32(va[dt], pf0[s], o[dt]);
; #pragma unroll
;         for (int dt = 0; dt < 4; ++dt) o[dt] = MFMA32(vb[dt], pf1[s], o[dt]);
;         __builtin_amdgcn_sched_barrier(0);
;     }
.Lmla_lsm_643_0:
	v_sub_f32_e32 v0, v96, v183
	v_exp_f32_e32 v15, v0
	v_sub_f32_e32 v0, v80, v183
	v_sub_f32_e32 v2, v98, v183
	v_exp_f32_e32 v185, v0
	v_sub_f32_e32 v0, v97, v183
	v_exp_f32_e32 v97, v2
	v_sub_f32_e32 v2, v82, v183
	v_exp_f32_e32 v187, v2
	v_sub_f32_e32 v2, v99, v183
	v_exp_f32_e32 v96, v2
	v_sub_f32_e32 v2, v83, v183
	v_exp_f32_e32 v98, v2
	v_sub_f32_e32 v2, v100, v183
	v_exp_f32_e32 v186, v2
	v_sub_f32_e32 v2, v84, v183
	v_exp_f32_e32 v189, v2
	v_sub_f32_e32 v2, v101, v183
	v_exp_f32_e32 v84, v2
	v_sub_f32_e32 v2, v85, v183
	v_exp_f32_e32 v100, v2
	v_sub_f32_e32 v2, v102, v183
	v_exp_f32_e32 v188, v2
	v_sub_f32_e32 v2, v86, v183
	v_exp_f32_e32 v191, v2
	v_sub_f32_e32 v2, v103, v183
	v_exp_f32_e32 v86, v2
	v_sub_f32_e32 v2, v87, v183
	v_exp_f32_e32 v102, v2
	v_sub_f32_e32 v2, v104, v183
	v_exp_f32_e32 v190, v2
	v_sub_f32_e32 v2, v88, v183
	v_exp_f32_e32 v193, v2
	v_sub_f32_e32 v2, v105, v183
	v_exp_f32_e32 v88, v2
	v_sub_f32_e32 v2, v89, v183
	v_exp_f32_e32 v104, v2
	v_sub_f32_e32 v2, v106, v183
	v_exp_f32_e32 v192, v2
	v_sub_f32_e32 v2, v90, v183
	v_exp_f32_e32 v195, v2
	v_sub_f32_e32 v2, v107, v183
	v_exp_f32_e32 v90, v2
	v_sub_f32_e32 v2, v91, v183
	v_exp_f32_e32 v106, v2
	v_sub_f32_e32 v2, v108, v183
	v_exp_f32_e32 v194, v2
	v_sub_f32_e32 v2, v92, v183
	v_exp_f32_e32 v197, v2
	v_sub_f32_e32 v2, v109, v183
	v_exp_f32_e32 v92, v2
	v_sub_f32_e32 v2, v93, v183
	v_exp_f32_e32 v108, v2
	v_sub_f32_e32 v2, v110, v183
	v_exp_f32_e32 v196, v2
	v_sub_f32_e32 v2, v94, v183
	v_exp_f32_e32 v198, v2
	v_sub_f32_e32 v2, v111, v183
	v_exp_f32_e32 v14, v0
	v_sub_f32_e32 v0, v81, v183
	v_exp_f32_e32 v94, v2
	v_sub_f32_e32 v2, v95, v183
	v_exp_f32_e32 v0, v0
	v_exp_f32_e32 v110, v2
	v_cvt_pk_bf16_f32 v80, v15, v14
	v_cvt_pk_bf16_f32 v81, v97, v96
	v_cvt_pk_bf16_f32 v82, v186, v84
	v_cvt_pk_bf16_f32 v83, v188, v86
	v_cvt_pk_bf16_f32 v6, v185, v0
	v_cvt_pk_bf16_f32 v7, v187, v98
	v_cvt_pk_bf16_f32 v8, v189, v100
	v_cvt_pk_bf16_f32 v9, v191, v102
	v_cvt_pk_bf16_f32 v10, v190, v88
	v_cvt_pk_bf16_f32 v11, v192, v90
	v_cvt_pk_bf16_f32 v12, v194, v92
	v_cvt_pk_bf16_f32 v13, v196, v94
	v_cvt_pk_bf16_f32 v2, v193, v104
	v_cvt_pk_bf16_f32 v3, v195, v106
	v_cvt_pk_bf16_f32 v4, v197, v108
	v_cvt_pk_bf16_f32 v5, v198, v110
	v_add_f32_e32 v85, v15, v185
	v_add_f32_e32 v87, v14, v0
	v_add_f32_e32 v89, v97, v187
	v_add_f32_e32 v91, v96, v98
	v_add_f32_e32 v85, v85, v186
	v_add_f32_e32 v87, v87, v189
	v_add_f32_e32 v89, v89, v84
	v_add_f32_e32 v91, v91, v100
	v_add_f32_e32 v85, v85, v188
	v_add_f32_e32 v87, v87, v191
	v_add_f32_e32 v89, v89, v86
	v_add_f32_e32 v91, v91, v102
	v_add_f32_e32 v85, v85, v190
	v_add_f32_e32 v87, v87, v193
	v_add_f32_e32 v89, v89, v88
	v_add_f32_e32 v91, v91, v104
	v_add_f32_e32 v85, v85, v192
	v_add_f32_e32 v87, v87, v195
	v_add_f32_e32 v89, v89, v90
	v_add_f32_e32 v91, v91, v106
	v_add_f32_e32 v85, v85, v194
	v_add_f32_e32 v87, v87, v197
	v_add_f32_e32 v89, v89, v92
	v_add_f32_e32 v91, v91, v108
	v_add_f32_e32 v85, v85, v196
	v_add_f32_e32 v87, v87, v198
	v_add_f32_e32 v89, v89, v94
	v_add_f32_e32 v91, v91, v110
	v_add_f32_e32 v85, v85, v87
	v_add_f32_e32 v89, v89, v91
	v_add_f32_e32 v85, v85, v89
	v_add_f32_e32 v175, v175, v85
	s_cmp_eq_u32 s101, 1
	s_cbranch_scc1 .Lmla_lsm_ret_post_0
	s_add_i32 s90, s89, 0xffff5400
	s_cmp_lg_u32 s73, 0
	s_cselect_b32 s73, s90, 0x15800
	v_add_u32_e32 v0, s73, v182
	ds_read_b128 v[84:87], v0 offset:25600
	ds_read_b128 v[88:91], v0 offset:25664
	ds_read_b128 v[92:95], v0 offset:30208
	ds_read_b128 v[96:99], v0 offset:30272
	ds_read_b128 v[100:103], v0 offset:34816
	ds_read_b128 v[104:107], v0 offset:34880
	ds_read_b128 v[108:111], v0 offset:39424
	ds_read_b128 v[186:189], v0 offset:39488
	ds_read_b128 v[200:203], v0 offset:25616
	ds_read_b128 v[204:207], v0 offset:25680
	ds_read_b128 v[208:211], v0 offset:30224
	ds_read_b128 v[212:215], v0 offset:30288
	ds_read_b128 v[216:219], v0 offset:34832
	ds_read_b128 v[220:223], v0 offset:34896
	ds_read_b128 v[224:227], v0 offset:39440
	ds_read_b128 v[228:231], v0 offset:39504
	s_cmp_ge_u32 s88, s74
	s_cbranch_scc1 .Lmla_pvplain_0
	s_mul_i32 s91, s76, 0xac00
	s_waitcnt lgkmcnt(8)
	v_mfma_f32_32x32x16_bf16 v[64:79], v[84:87], v[80:83], v[64:79]
	v_readlane_b32 s90, v255, 11
	v_lshl_add_u32 v253, s88, v176, v166
	s_add_i32 m0, s91, s90
	s_nop 0
	global_load_lds_dwordx4 v253, s[12:13]
	v_mfma_f32_32x32x16_bf16 v[48:63], v[92:95], v[80:83], v[48:63]
	v_mfma_f32_32x32x16_bf16 v[32:47], v[100:103], v[80:83], v[32:47]
	v_lshl_add_u32 v253, s88, v177, v167
	s_add_i32 m0, s91, s85
	s_nop 0
	global_load_lds_dwordx4 v253, s[12:13]
	v_mfma_f32_32x32x16_bf16 v[16:31], v[108:111], v[80:83], v[16:31]
	v_mfma_f32_32x32x16_bf16 v[64:79], v[88:91], v[6:9], v[64:79]
	v_lshl_add_u32 v253, s88, v178, v168
	s_add_i32 m0, s91, s72
	s_nop 0
	global_load_lds_dwordx4 v253, s[12:13]
	v_mfma_f32_32x32x16_bf16 v[48:63], v[96:99], v[6:9], v[48:63]
	v_mfma_f32_32x32x16_bf16 v[32:47], v[104:107], v[6:9], v[32:47]
	v_lshl_add_u32 v253, s88, v179, v169
	s_add_i32 m0, s91, s75
	s_nop 0
	global_load_lds_dwordx4 v253, s[12:13]
	v_mfma_f32_32x32x16_bf16 v[16:31], v[186:189], v[6:9], v[16:31]
	s_waitcnt lgkmcnt(0)
	v_mfma_f32_32x32x16_bf16 v[64:79], v[200:203], v[10:13], v[64:79]
	v_lshl_add_u32 v253, s88, v180, v170
	s_add_i32 m0, s91, s1
	s_nop 0
	global_load_lds_dwordx4 v253, s[12:13]
	v_mfma_f32_32x32x16_bf16 v[48:63], v[208:211], v[10:13], v[48:63]
	v_mfma_f32_32x32x16_bf16 v[32:47], v[216:219], v[10:13], v[32:47]
	s_andn2_b64 vcc, exec, s[94:95]
	s_cbranch_vccnz .Lmla_a5_pv_0
	v_readlane_b32 s90, v255, 9
	v_lshl_add_u32 v253, s88, v181, v171
	s_add_i32 m0, s91, s90
	s_nop 0
	global_load_lds_dwordx4 v253, s[12:13]

; #define LAS __attribute__((address_space(3)))
; DI f32x16 zero16() { f32x16 z; for (int i = 0; i < 16; ++i) z[i] = 0.f; return z; }
; #define MFMA32(a, b, c) __builtin_amdgcn_mfma_f32_32x32x16_bf16((a), (b), (c), 0, 0, 0)
; DI void mla_s_softmax(const LAS unsigned char* base, int r, int h, bool is_diag, int lim, const bf16x8 (&qf)[12], f32x16 (&o)[4], float& m_run, float& l_run,
;                       bf16x8 (&pf0)[2], bf16x8 (&pf1)[2]) {
;     f32x16 s0 = zero16(), s1 = zero16();
;     const LAS unsigned char* kp = base + r * MLA_KROW + h * 16;
; #pragma unroll
;     for (int g = 0; g < 3; ++g) {
;         bf16x8 fa[4], fb[4];
; #pragma unroll
;         for (int j = 0; j < 4; ++j) { fa[j] = *(const LAS bf16x8*)(kp + (4 * g + j) * 32); fb[j] = *(const LAS bf16x8*)(kp + 32 * MLA_KROW + (4 * g + j) * 32); }
;         __builtin_amdgcn_sched_barrier(0);
; #pragma unroll
;         for (int j = 0; j < 4; ++j) { s0 = MFMA32(fa[j], qf[4 * g + j], s0); s1 = MFMA32(fb[j], qf[4 * g + j], s1); }
;         __builtin_amdgcn_sched_barrier(0);
;     }
.Lmla_splain_0:
	ds_read_b128 v[2:5], v0
	ds_read_b128 v[6:9], v0 offset:32
	ds_read_b128 v[10:13], v0 offset:12800
	ds_read_b128 v[186:189], v0 offset:12832
	ds_read_b128 v[190:193], v0 offset:64
	ds_read_b128 v[194:197], v0 offset:96
	ds_read_b128 v[198:201], v0 offset:12864
	ds_read_b128 v[202:205], v0 offset:12896
	ds_read_b128 v[206:209], v0 offset:128
	ds_read_b128 v[210:213], v0 offset:160
	ds_read_b128 v[214:217], v0 offset:12928
	ds_read_b128 v[218:221], v0 offset:12960
	ds_read_b128 v[222:225], v0 offset:192
	ds_read_b128 v[226:229], v0 offset:224
	ds_read_b128 v[230:233], v0 offset:12992
	ds_read_b128 v[234:237], v0 offset:13024
	s_cmp_lg_u32 s33, s77
	s_waitcnt lgkmcnt(8)
	v_mfma_f32_32x32x16_bf16 v[96:111], v[2:5], v[112:115], 0
	v_mfma_f32_32x32x16_bf16 v[80:95], v[10:13], v[112:115], 0
	v_mfma_f32_32x32x16_bf16 v[96:111], v[6:9], v[116:119], v[96:111]
	v_mfma_f32_32x32x16_bf16 v[80:95], v[186:189], v[116:119], v[80:95]
	v_mfma_f32_32x32x16_bf16 v[96:111], v[190:193], v[120:123], v[96:111]
	v_mfma_f32_32x32x16_bf16 v[80:95], v[198:201], v[120:123], v[80:95]
	v_mfma_f32_32x32x16_bf16 v[96:111], v[194:197], v[124:127], v[96:111]
	v_mfma_f32_32x32x16_bf16 v[80:95], v[202:205], v[124:127], v[80:95]
	ds_read_b128 v[2:5], v0 offset:256
	ds_read_b128 v[6:9], v0 offset:288
	ds_read_b128 v[10:13], v0 offset:13056
	ds_read_b128 v[186:189], v0 offset:13088
	ds_read_b128 v[190:193], v0 offset:320
	ds_read_b128 v[194:197], v0 offset:352
	ds_read_b128 v[198:201], v0 offset:13120
	ds_read_b128 v[202:205], v0 offset:13152
	s_waitcnt lgkmcnt(8)
	v_mfma_f32_32x32x16_bf16 v[96:111], v[206:209], v[128:131], v[96:111]
	v_mfma_f32_32x32x16_bf16 v[80:95], v[214:217], v[128:131], v[80:95]
	v_mfma_f32_32x32x16_bf16 v[96:111], v[210:213], v[132:135], v[96:111]
	v_mfma_f32_32x32x16_bf16 v[80:95], v[218:221], v[132:135], v[80:95]
	v_mfma_f32_32x32x16_bf16 v[96:111], v[222:225], v[136:139], v[96:111]
	v_mfma_f32_32x32x16_bf16 v[80:95], v[230:233], v[136:139], v[80:95]
	v_mfma_f32_32x32x16_bf16 v[96:111], v[226:229], v[140:143], v[96:111]
	v_mfma_f32_32x32x16_bf16 v[80:95], v[234:237], v[140:143], v[80:95]
	s_waitcnt lgkmcnt(0)
	v_mfma_f32_32x32x16_bf16 v[96:111], v[2:5], v[144:147], v[96:111]
	v_mfma_f32_32x32x16_bf16 v[80:95], v[10:13], v[144:147], v[80:95]
	v_mfma_f32_32x32x16_bf16 v[96:111], v[6:9], v[148:151], v[96:111]
	v_mfma_f32_32x32x16_bf16 v[80:95], v[186:189], v[148:151], v[80:95]
	v_mfma_f32_32x32x16_bf16 v[96:111], v[190:193], v[152:155], v[96:111]
	v_mfma_f32_32x32x16_bf16 v[80:95], v[198:201], v[152:155], v[80:95]
	v_mfma_f32_32x32x16_bf16 v[96:111], v[194:197], v[156:159], v[96:111]
	v_mfma_f32_32x32x16_bf16 v[80:95], v[202:205], v[156:159], v[80:95]
	s_andn2_b64 vcc, exec, s[2:3]
	s_cbranch_vccnz .Lmla_late_end_0
	s_cmp_lg_u32 s33, s77
	s_cbranch_scc1 .LBB0_641

; DI void mla_block(const Params& p, LAS unsigned char* lds, int b, int hd, int qb, int tid) {
;     ...
;     for (int kt = 0; kt < ntiles; ++kt) {
;         asm volatile("s_waitcnt vmcnt(0)" ::: "memory");
;         __builtin_amdgcn_s_barrier();
;         asm volatile("" ::: "memory");
;         const int bprev = bcur == 0 ? 2 : bcur - 1, bnext = bcur == 2 ? 0 : bcur + 1;
;         if (kt + 1 < ntiles) MLA_STAGE(kt + 1, bnext);
;         if (late && kt >= 1 && kt - 1 <= wlast) mla_pv(lds + bprev * MLA_BUF, r, h, pf0, pf1, o);
;         if (kt <= wlast) {
;             mla_s_softmax(lds + bcur * MLA_BUF, r, h, kt == wlast, q0 + r - kt * 64, qf, o, m_run, l_run, pf0, pf1);
;             if (!late) mla_pv(lds + bcur * MLA_BUF, r, h, pf0, pf1, o);
.Lmla_late_end_0:
	s_cmp_eq_u32 s0, s88
	s_cbranch_scc1 .LBB0_651

; #define LAS __attribute__((address_space(3)))
; #define MFMA32(a, b, c) __builtin_amdgcn_mfma_f32_32x32x16_bf16((a), (b), (c), 0, 0, 0)
; DI void mla_pv(const LAS unsigned char* base, int r, int h, const bf16x8 (&pf0)[2], const bf16x8 (&pf1)[2], f32x16 (&o)[4]) {
;     const LAS unsigned char* vp = base + MLA_KBYTES + r * MLA_VROW + h * 32;
; #pragma unroll
;     for (int s = 0; s < 2; ++s) {
;         bf16x8 va[4], vb[4];
; #pragma unroll
;         for (int dt = 0; dt < 4; ++dt) { va[dt] = *(const LAS bf16x8*)(vp + dt * 32 * MLA_VROW + s * 16); vb[dt] = *(const LAS bf16x8*)(vp + dt * 32 * MLA_VROW + 64 + s * 16); }
;         __builtin_amdgcn_sched_barrier(0);
; #pragma unroll
;         for (int dt = 0; dt < 4; ++dt) o[dt] = MFMA32(va[dt], pf0[s], o[dt]);
; #pragma unroll
;         for (int dt = 0; dt < 4; ++dt) o[dt] = MFMA32(vb[dt], pf1[s], o[dt]);
;         __builtin_amdgcn_sched_barrier(0);
;     }
; DI void mla_block(const Params& p, LAS unsigned char* lds, int b, int hd, int qb, int tid) {
;     ...
;     if (late && wlast == ntiles - 1) { const int bprev = bcur == 0 ? 2 : bcur - 1; mla_pv(lds + bprev * MLA_BUF, r, h, pf0, pf1, o); }
.LBB0_651:
	v_readlane_b32 s0, v255, 48
	s_or_b32 s0, s0, 3
	s_cmp_eq_u32 s33, s0
	s_cselect_b64 s[0:1], -1, 0
	s_and_b64 s[0:1], s[78:79], s[0:1]
	s_and_b64 vcc, exec, s[0:1]
	s_cbranch_vccz .LBB0_653
	s_mov_b32 s100, 1
	s_mov_b32 s101, 1
	s_branch .Lmla_lsm_0
.Lmla_lsm_ret_post_0:
	s_mul_i32 s0, s76, 0xac00
	s_add_i32 s0, s0, 0xffff5400
	s_cmp_lg_u32 s76, 0
	s_cselect_b32 s0, s0, 0x15800
	s_add_i32 s0, s0, 0
	v_add3_u32 v0, s0, v172, v173
	ds_read_b128 v[84:87], v0 offset:25600
	ds_read_b128 v[88:91], v0 offset:25664
	ds_read_b128 v[92:95], v0 offset:30208
	ds_read_b128 v[96:99], v0 offset:30272
	ds_read_b128 v[100:103], v0 offset:34816
	ds_read_b128 v[104:107], v0 offset:34880
	ds_read_b128 v[108:111], v0 offset:39424
	ds_read_b128 v[112:115], v0 offset:39488
	s_waitcnt lgkmcnt(0)
	v_mfma_f32_32x32x16_bf16 v[64:79], v[84:87], v[80:83], v[64:79]
	v_mfma_f32_32x32x16_bf16 v[48:63], v[92:95], v[80:83], v[48:63]
	v_mfma_f32_32x32x16_bf16 v[32:47], v[100:103], v[80:83], v[32:47]
	v_mfma_f32_32x32x16_bf16 v[16:31], v[108:111], v[80:83], v[16:31]
	v_mfma_f32_32x32x16_bf16 v[64:79], v[88:91], v[6:9], v[64:79]
	v_mfma_f32_32x32x16_bf16 v[48:63], v[96:99], v[6:9], v[48:63]
	v_mfma_f32_32x32x16_bf16 v[32:47], v[104:107], v[6:9], v[32:47]
	v_mfma_f32_32x32x16_bf16 v[16:31], v[112:115], v[6:9], v[16:31]
	ds_read_b128 v[6:9], v0 offset:25616
	ds_read_b128 v[80:83], v0 offset:25680
	ds_read_b128 v[84:87], v0 offset:30224
	ds_read_b128 v[88:91], v0 offset:30288
	ds_read_b128 v[92:95], v0 offset:34832
	ds_read_b128 v[96:99], v0 offset:34896
	ds_read_b128 v[100:103], v0 offset:39440
	ds_read_b128 v[104:107], v0 offset:39504
	s_waitcnt lgkmcnt(0)
	v_mfma_f32_32x32x16_bf16 v[64:79], v[6:9], v[10:13], v[64:79]
	v_mfma_f32_32x32x16_bf16 v[48:63], v[84:87], v[10:13], v[48:63]
	v_mfma_f32_32x32x16_bf16 v[32:47], v[92:95], v[10:13], v[32:47]
	v_mfma_f32_32x32x16_bf16 v[16:31], v[100:103], v[10:13], v[16:31]
	v_mfma_f32_32x32x16_bf16 v[64:79], v[80:83], v[2:5], v[64:79]
	v_mfma_f32_32x32x16_bf16 v[48:63], v[88:91], v[2:5], v[48:63]
	v_mfma_f32_32x32x16_bf16 v[32:47], v[96:99], v[2:5], v[32:47]
	v_mfma_f32_32x32x16_bf16 v[16:31], v[104:107], v[2:5], v[16:31]
